# MLA loader/consumer role split: waves 0-3 (leaders with barrier slack) stage both 32-row halves of the V tile plus the rope keys, waves 4-7 only their K rows (1 staging load per tile instead of 3)
# baseline (speedup 1.0000x reference)
.Lmla_p_nomask:
	v_max3_f32 v251, v64, v65, v66
	v_max3_f32 v251, v251, v67, v68
	v_max3_f32 v251, v251, v69, v70
	v_max3_f32 v251, v251, v71, v72
	v_max3_f32 v251, v251, v73, v74
	v_max3_f32 v251, v251, v75, v76
	v_max3_f32 v251, v251, v77, v78
	v_max_f32_e32 v251, v251, v79
	v_max3_f32 v252, v80, v81, v82
	v_max3_f32 v252, v252, v83, v84
	v_max3_f32 v252, v252, v85, v86
	v_max3_f32 v252, v252, v87, v88
	v_max3_f32 v252, v252, v89, v90
	v_max3_f32 v252, v252, v91, v92
	v_max3_f32 v252, v252, v93, v94
	v_max_f32_e32 v252, v252, v95
	v_max_f32_e32 v251, v251, v252
	v_mov_b32_e32 v252, v251
	s_nop 1
	v_permlane32_swap_b32_e32 v251, v252
	v_max_f32_e32 v251, v251, v252
	v_mov_b32_e32 v212, v251
	v_sub_f32_e32 v64, v64, v251
	v_sub_f32_e32 v65, v65, v251
	v_sub_f32_e32 v66, v66, v251
	v_sub_f32_e32 v67, v67, v251
	v_sub_f32_e32 v68, v68, v251
	v_sub_f32_e32 v69, v69, v251
	v_sub_f32_e32 v70, v70, v251
	v_sub_f32_e32 v71, v71, v251
	v_sub_f32_e32 v72, v72, v251
	v_sub_f32_e32 v73, v73, v251
	v_sub_f32_e32 v74, v74, v251
	v_sub_f32_e32 v75, v75, v251
	v_sub_f32_e32 v76, v76, v251
	v_sub_f32_e32 v77, v77, v251
	v_sub_f32_e32 v78, v78, v251
	v_sub_f32_e32 v79, v79, v251
	v_sub_f32_e32 v80, v80, v251
	v_sub_f32_e32 v81, v81, v251
	v_sub_f32_e32 v82, v82, v251
	v_sub_f32_e32 v83, v83, v251
	v_sub_f32_e32 v84, v84, v251
	v_sub_f32_e32 v85, v85, v251
	v_sub_f32_e32 v86, v86, v251
	v_sub_f32_e32 v87, v87, v251
	v_sub_f32_e32 v88, v88, v251
	v_sub_f32_e32 v89, v89, v251
	v_sub_f32_e32 v90, v90, v251
	v_sub_f32_e32 v91, v91, v251
	v_sub_f32_e32 v92, v92, v251
	v_sub_f32_e32 v93, v93, v251
	v_sub_f32_e32 v94, v94, v251
	v_sub_f32_e32 v95, v95, v251
	v_xor_b32_e32 v48, 0x80000000, v251
	v_mov_b32_e32 v49, v48
	v_mov_b32_e32 v50, v48
	v_mov_b32_e32 v51, v48
	v_mov_b32_e32 v52, v48
	v_mov_b32_e32 v53, v48
	v_mov_b32_e32 v54, v48
	v_mov_b32_e32 v55, v48
	v_mov_b32_e32 v56, v48
	v_mov_b32_e32 v57, v48
	v_mov_b32_e32 v58, v48
	v_mov_b32_e32 v59, v48
	v_mov_b32_e32 v60, v48
	v_mov_b32_e32 v61, v48
	v_mov_b32_e32 v62, v48
	v_mov_b32_e32 v63, v48
	s_mov_b64 s[6:7], 0x30000
	v_lshl_add_u64 v[200:201], v[192:193], 0, s[6:7]
	global_load_dwordx4 v[222:225], v[200:201], off
	s_waitcnt lgkmcnt(0)
	s_barrier
	s_cmp_lt_u32 s39, 4
	s_cbranch_scc0 .Lmla_loopb
.Lmla_loopa:
.Lmla_it0a:
	s_add_i32 s42, s65, 3
	s_min_u32 s42, s42, s44
	s_lshl_b64 s[6:7], s[42:43], 17
	v_lshl_add_u64 v[242:243], v[190:191], 0, s[6:7]
	s_lshl_b64 s[6:7], s[42:43], 12
	v_lshl_add_u64 v[244:245], v[194:195], 0, s[6:7]
	s_add_i32 s42, s65, 2
	s_min_u32 s42, s42, s44
	s_lshl_b64 s[6:7], s[42:43], 17
	v_lshl_add_u64 v[246:247], v[192:193], 0, s[6:7]
	s_mov_b64 s[4:5], 0x10000
	v_lshl_add_u64 v[200:201], v[246:247], 0, s[4:5]
	global_load_dwordx4 v[6:9], v[242:243], off
	global_load_dwordx4 v[10:13], v[246:247], off
	global_load_dwordx4 v[218:221], v[200:201], off
	global_load_dwordx4 v[2:5], v[244:245], off
	s_cmp_ge_u32 s65, s45
	s_cbranch_scc1 .Lmla_skip0a
	s_add_i32 s41, s65, 1
	s_cmp_ge_u32 s41, s64
	s_cselect_b32 s7, 1, 0
	s_cmp_lt_u32 s41, s45
	s_cselect_b32 s26, 1, 0
	s_and_b32 s56, s7, s26
	s_lshl_b32 s27, s41, 6
	ds_read_b128 v[164:167], v210 offset:25600
	ds_read_b128 v[168:171], v210 offset:25632
	ds_read_b128 v[172:175], v210 offset:25664
	ds_read_b128 v[214:217], v210 offset:25696
	s_setprio 3
	v_exp_f32_e32 v64, v64
	v_exp_f32_e32 v65, v65
	v_exp_f32_e32 v66, v66
	v_exp_f32_e32 v67, v67
	s_waitcnt lgkmcnt(3)
	v_mfma_f32_32x32x16_bf16 v[132:147], v[164:167], v[96:99], v[48:63]
	ds_read_b128 v[164:167], v210 offset:25728
	v_add_f32_e32 v14, v64, v65
	v_add_f32_e32 v15, v66, v67
	v_exp_f32_e32 v68, v68
	v_exp_f32_e32 v69, v69
	s_waitcnt lgkmcnt(3)
	v_mfma_f32_32x32x16_bf16 v[132:147], v[168:171], v[100:103], v[132:147]
	ds_read_b128 v[168:171], v210 offset:25760
	v_exp_f32_e32 v70, v70
	v_exp_f32_e32 v71, v71
	v_add_f32_e32 v14, v14, v15
	v_add_f32_e32 v15, v68, v69
	s_waitcnt lgkmcnt(3)
	v_mfma_f32_32x32x16_bf16 v[132:147], v[172:175], v[104:107], v[132:147]
	ds_read_b128 v[172:175], v210 offset:32256
	v_add_f32_e32 v213, v70, v71
	v_cvt_pk_bf16_f32 v64, v64, v65
	v_cvt_pk_bf16_f32 v65, v66, v67
	v_cvt_pk_bf16_f32 v66, v68, v69
	v_cvt_pk_bf16_f32 v67, v70, v71
	s_waitcnt lgkmcnt(3)
	v_mfma_f32_32x32x16_bf16 v[132:147], v[214:217], v[108:111], v[132:147]
	ds_read_b128 v[214:217], v210 offset:32288
	v_exp_f32_e32 v72, v72
	v_exp_f32_e32 v73, v73
	v_exp_f32_e32 v74, v74
	v_exp_f32_e32 v75, v75
	s_waitcnt lgkmcnt(3)
	v_mfma_f32_32x32x16_bf16 v[132:147], v[164:167], v[112:115], v[132:147]
	ds_read_b128 v[164:167], v210 offset:32320
	v_add_f32_e32 v14, v14, v15
	v_add_f32_e32 v14, v14, v213
	v_exp_f32_e32 v76, v76
	v_exp_f32_e32 v77, v77
	s_setprio 2
	s_waitcnt lgkmcnt(3)
	v_mfma_f32_32x32x16_bf16 v[132:147], v[168:171], v[116:119], v[132:147]
	ds_read_b128 v[168:171], v210 offset:32352
	v_exp_f32_e32 v78, v78
	v_exp_f32_e32 v79, v79
	v_add_f32_e32 v15, v72, v73
	v_add_f32_e32 v213, v74, v75
	s_waitcnt lgkmcnt(3)
	v_mfma_f32_32x32x16_bf16 v[148:163], v[172:175], v[96:99], v[48:63]
	ds_read_b128 v[172:175], v210 offset:32384
	ds_read_b64_tr_b16 v[226:227], v211 offset:13312
	ds_read_b64_tr_b16 v[228:229], v211 offset:14848
	v_add_f32_e32 v248, v76, v77
	v_add_f32_e32 v249, v78, v79
	v_cvt_pk_bf16_f32 v68, v72, v73
	v_cvt_pk_bf16_f32 v69, v74, v75
	v_cvt_pk_bf16_f32 v70, v76, v77
	v_cvt_pk_bf16_f32 v71, v78, v79
	s_waitcnt lgkmcnt(5)
	v_mfma_f32_32x32x16_bf16 v[148:163], v[214:217], v[100:103], v[148:163]
	ds_read_b128 v[214:217], v210 offset:32416
	ds_read_b64_tr_b16 v[230:231], v211 offset:13376
	ds_read_b64_tr_b16 v[232:233], v211 offset:14912
	v_add_f32_e32 v15, v15, v213
	v_add_f32_e32 v248, v248, v249
	v_exp_f32_e32 v80, v80
	v_exp_f32_e32 v81, v81
	s_waitcnt lgkmcnt(7)
	v_mfma_f32_32x32x16_bf16 v[148:163], v[164:167], v[104:107], v[148:163]
	ds_read_b64_tr_b16 v[234:235], v211 offset:16384
	ds_read_b64_tr_b16 v[236:237], v211 offset:17920
	v_exp_f32_e32 v82, v82
	v_exp_f32_e32 v83, v83
	v_add_f32_e32 v14, v14, v15
	v_add_f32_e32 v14, v14, v248
	s_waitcnt lgkmcnt(8)
	v_mfma_f32_32x32x16_bf16 v[148:163], v[168:171], v[108:111], v[148:163]
	ds_read_b64_tr_b16 v[238:239], v211 offset:16448
	ds_read_b64_tr_b16 v[240:241], v211 offset:17984
	v_add_f32_e32 v15, v80, v81
	v_add_f32_e32 v213, v82, v83
	v_exp_f32_e32 v84, v84
	v_exp_f32_e32 v85, v85
	s_setprio 1
	s_waitcnt lgkmcnt(9)
	v_mfma_f32_32x32x16_bf16 v[148:163], v[172:175], v[112:115], v[148:163]
	v_exp_f32_e32 v86, v86
	v_exp_f32_e32 v87, v87
	v_add_f32_e32 v15, v15, v213
	v_add_f32_e32 v213, v84, v85
	s_waitcnt lgkmcnt(6)
	v_mfma_f32_32x32x16_bf16 v[148:163], v[214:217], v[116:119], v[148:163]
	v_add_f32_e32 v248, v86, v87
	v_cvt_pk_bf16_f32 v80, v80, v81
	v_cvt_pk_bf16_f32 v81, v82, v83
	v_cvt_pk_bf16_f32 v82, v84, v85
	v_cvt_pk_bf16_f32 v83, v86, v87
	v_mfma_f32_32x32x16_bf16 v[32:47], v[226:229], v[64:67], v[32:47]
	ds_read_b64_tr_b16 v[226:227], v211 offset:19456
	ds_read_b64_tr_b16 v[228:229], v211 offset:20992
	v_exp_f32_e32 v88, v88
	v_exp_f32_e32 v89, v89
	v_exp_f32_e32 v90, v90
	v_exp_f32_e32 v91, v91
	s_waitcnt lgkmcnt(6)
	v_mfma_f32_32x32x16_bf16 v[16:31], v[230:233], v[64:67], v[16:31]
	ds_read_b64_tr_b16 v[230:231], v211 offset:19520
	ds_read_b64_tr_b16 v[232:233], v211 offset:21056
	v_add_f32_e32 v213, v213, v248
	v_add_f32_e32 v15, v15, v213
	v_exp_f32_e32 v92, v92
	v_exp_f32_e32 v93, v93
	s_waitcnt lgkmcnt(6)
	v_mfma_f32_32x32x16_bf16 v[32:47], v[234:237], v[68:71], v[32:47]
	ds_read_b64_tr_b16 v[234:235], v211 offset:22528
	ds_read_b64_tr_b16 v[236:237], v211 offset:24064
	v_exp_f32_e32 v94, v94
	v_exp_f32_e32 v95, v95
	v_add_f32_e32 v213, v88, v89
	v_add_f32_e32 v248, v90, v91
	s_setprio 0
	s_waitcnt lgkmcnt(6)
	v_mfma_f32_32x32x16_bf16 v[16:31], v[238:241], v[68:71], v[16:31]
	ds_read_b64_tr_b16 v[238:239], v211 offset:22592
	ds_read_b64_tr_b16 v[240:241], v211 offset:24128
	s_cmp_lg_u32 s56, 0
	s_cbranch_scc1 .Lmla_mask0a
.Lmla_maskret0a:
	v_add_f32_e32 v249, v92, v93
	v_add_f32_e32 v250, v94, v95
	v_cvt_pk_bf16_f32 v84, v88, v89
	v_cvt_pk_bf16_f32 v85, v90, v91
	v_cvt_pk_bf16_f32 v86, v92, v93
	v_cvt_pk_bf16_f32 v87, v94, v95
	s_waitcnt lgkmcnt(6)
	v_mfma_f32_32x32x16_bf16 v[32:47], v[226:229], v[80:83], v[32:47]
	v_add_f32_e32 v213, v213, v248
	v_add_f32_e32 v249, v249, v250
	v_add_f32_e32 v14, v14, v15
	v_max3_f32 v251, v132, v133, v134
	v_max3_f32 v251, v251, v135, v136
	s_waitcnt lgkmcnt(4)
	v_mfma_f32_32x32x16_bf16 v[16:31], v[230:233], v[80:83], v[16:31]
	s_waitcnt vmcnt(4)
	ds_write_b128 v205, v[120:123] offset:0
	ds_write_b128 v206, v[124:127] offset:38912
	ds_write_b128 v206, v[222:225] offset:45056
	v_add_f32_e32 v213, v213, v249
	v_add_f32_e32 v14, v14, v213
	v_add_f32_e32 v209, v209, v14
	v_max3_f32 v251, v251, v137, v138
	v_max3_f32 v251, v251, v139, v140
	v_max3_f32 v251, v251, v141, v142
	s_waitcnt lgkmcnt(5)
	v_mfma_f32_32x32x16_bf16 v[32:47], v[234:237], v[84:87], v[32:47]
	v_max3_f32 v251, v251, v143, v144
	v_max3_f32 v251, v251, v145, v146
	v_max_f32_e32 v251, v251, v147
	v_max3_f32 v252, v148, v149, v150
	v_max3_f32 v252, v252, v151, v152
	s_waitcnt lgkmcnt(3)
	v_mfma_f32_32x32x16_bf16 v[16:31], v[238:241], v[84:87], v[16:31]
	ds_write_b128 v207, v[128:131] offset:128
	v_max3_f32 v252, v252, v153, v154
	v_max3_f32 v252, v252, v155, v156
	v_max3_f32 v252, v252, v157, v158
	v_max3_f32 v252, v252, v159, v160
	v_max3_f32 v252, v252, v161, v162
	v_max_f32_e32 v252, v252, v163
	v_max_f32_e32 v251, v251, v252
	v_mov_b32_e32 v252, v251
	s_nop 1
	v_permlane32_swap_b32_e32 v251, v252
	v_max_f32_e32 v251, v251, v252
	v_cmp_lt_f32_e32 vcc, 0x41000000, v251
	s_cmp_lg_u32 s26, 0
	s_cbranch_scc0 .Lmla_nr0a
	s_cbranch_vccnz .Lmla_rare0a

.Lmla_end0a:
.Lmla_it1a:
	s_add_i32 s66, s65, 1
	s_add_i32 s42, s66, 3
	s_min_u32 s42, s42, s44
	s_lshl_b64 s[6:7], s[42:43], 17
	v_lshl_add_u64 v[242:243], v[190:191], 0, s[6:7]
	s_lshl_b64 s[6:7], s[42:43], 12
	v_lshl_add_u64 v[244:245], v[194:195], 0, s[6:7]
	s_add_i32 s42, s66, 2
	s_min_u32 s42, s42, s44
	s_lshl_b64 s[6:7], s[42:43], 17
	v_lshl_add_u64 v[246:247], v[192:193], 0, s[6:7]
	s_mov_b64 s[4:5], 0x10000
	v_lshl_add_u64 v[200:201], v[246:247], 0, s[4:5]
	global_load_dwordx4 v[120:123], v[242:243], off
	global_load_dwordx4 v[124:127], v[246:247], off
	global_load_dwordx4 v[222:225], v[200:201], off
	global_load_dwordx4 v[128:131], v[244:245], off
	s_cmp_ge_u32 s66, s45
	s_cbranch_scc1 .Lmla_skip1a
	s_add_i32 s41, s66, 1
	s_cmp_ge_u32 s41, s64
	s_cselect_b32 s7, 1, 0
	s_cmp_lt_u32 s41, s45
	s_cselect_b32 s26, 1, 0
	s_and_b32 s56, s7, s26
	s_lshl_b32 s27, s41, 6
	ds_read_b128 v[164:167], v210 offset:0
	ds_read_b128 v[168:171], v210 offset:32
	ds_read_b128 v[172:175], v210 offset:64
	ds_read_b128 v[214:217], v210 offset:96
	s_setprio 3
	v_exp_f32_e32 v132, v132
	v_exp_f32_e32 v133, v133
	v_exp_f32_e32 v134, v134
	v_exp_f32_e32 v135, v135
	s_waitcnt lgkmcnt(3)
	v_mfma_f32_32x32x16_bf16 v[64:79], v[164:167], v[96:99], v[48:63]
	ds_read_b128 v[164:167], v210 offset:128
	v_add_f32_e32 v14, v132, v133
	v_add_f32_e32 v15, v134, v135
	v_exp_f32_e32 v136, v136
	v_exp_f32_e32 v137, v137
	s_waitcnt lgkmcnt(3)
	v_mfma_f32_32x32x16_bf16 v[64:79], v[168:171], v[100:103], v[64:79]
	ds_read_b128 v[168:171], v210 offset:160
	v_exp_f32_e32 v138, v138
	v_exp_f32_e32 v139, v139
	v_add_f32_e32 v14, v14, v15
	v_add_f32_e32 v15, v136, v137
	s_waitcnt lgkmcnt(3)
	v_mfma_f32_32x32x16_bf16 v[64:79], v[172:175], v[104:107], v[64:79]
	ds_read_b128 v[172:175], v210 offset:6656
	v_add_f32_e32 v213, v138, v139
	v_cvt_pk_bf16_f32 v132, v132, v133
	v_cvt_pk_bf16_f32 v133, v134, v135
	v_cvt_pk_bf16_f32 v134, v136, v137
	v_cvt_pk_bf16_f32 v135, v138, v139
	s_waitcnt lgkmcnt(3)
	v_mfma_f32_32x32x16_bf16 v[64:79], v[214:217], v[108:111], v[64:79]
	ds_read_b128 v[214:217], v210 offset:6688
	v_exp_f32_e32 v140, v140
	v_exp_f32_e32 v141, v141
	v_exp_f32_e32 v142, v142
	v_exp_f32_e32 v143, v143
	s_waitcnt lgkmcnt(3)
	v_mfma_f32_32x32x16_bf16 v[64:79], v[164:167], v[112:115], v[64:79]
	ds_read_b128 v[164:167], v210 offset:6720
	v_add_f32_e32 v14, v14, v15
	v_add_f32_e32 v14, v14, v213
	v_exp_f32_e32 v144, v144
	v_exp_f32_e32 v145, v145
	s_setprio 2
	s_waitcnt lgkmcnt(3)
	v_mfma_f32_32x32x16_bf16 v[64:79], v[168:171], v[116:119], v[64:79]
	ds_read_b128 v[168:171], v210 offset:6752
	v_exp_f32_e32 v146, v146
	v_exp_f32_e32 v147, v147
	v_add_f32_e32 v15, v140, v141
	v_add_f32_e32 v213, v142, v143
	s_waitcnt lgkmcnt(3)
	v_mfma_f32_32x32x16_bf16 v[80:95], v[172:175], v[96:99], v[48:63]
	ds_read_b128 v[172:175], v210 offset:6784
	ds_read_b64_tr_b16 v[226:227], v211 offset:38912
	ds_read_b64_tr_b16 v[228:229], v211 offset:40448
	v_add_f32_e32 v248, v144, v145
	v_add_f32_e32 v249, v146, v147
	v_cvt_pk_bf16_f32 v136, v140, v141
	v_cvt_pk_bf16_f32 v137, v142, v143
	v_cvt_pk_bf16_f32 v138, v144, v145
	v_cvt_pk_bf16_f32 v139, v146, v147
	s_waitcnt lgkmcnt(5)
	v_mfma_f32_32x32x16_bf16 v[80:95], v[214:217], v[100:103], v[80:95]
	ds_read_b128 v[214:217], v210 offset:6816
	ds_read_b64_tr_b16 v[230:231], v211 offset:38976
	ds_read_b64_tr_b16 v[232:233], v211 offset:40512
	v_add_f32_e32 v15, v15, v213
	v_add_f32_e32 v248, v248, v249
	v_exp_f32_e32 v148, v148
	v_exp_f32_e32 v149, v149
	s_waitcnt lgkmcnt(7)
	v_mfma_f32_32x32x16_bf16 v[80:95], v[164:167], v[104:107], v[80:95]
	ds_read_b64_tr_b16 v[234:235], v211 offset:41984
	ds_read_b64_tr_b16 v[236:237], v211 offset:43520
	v_exp_f32_e32 v150, v150
	v_exp_f32_e32 v151, v151
	v_add_f32_e32 v14, v14, v15
	v_add_f32_e32 v14, v14, v248
	s_waitcnt lgkmcnt(8)
	v_mfma_f32_32x32x16_bf16 v[80:95], v[168:171], v[108:111], v[80:95]
	ds_read_b64_tr_b16 v[238:239], v211 offset:42048
	ds_read_b64_tr_b16 v[240:241], v211 offset:43584
	v_add_f32_e32 v15, v148, v149
	v_add_f32_e32 v213, v150, v151
	v_exp_f32_e32 v152, v152
	v_exp_f32_e32 v153, v153
	s_setprio 1
	s_waitcnt lgkmcnt(9)
	v_mfma_f32_32x32x16_bf16 v[80:95], v[172:175], v[112:115], v[80:95]
	v_exp_f32_e32 v154, v154
	v_exp_f32_e32 v155, v155
	v_add_f32_e32 v15, v15, v213
	v_add_f32_e32 v213, v152, v153
	s_waitcnt lgkmcnt(6)
	v_mfma_f32_32x32x16_bf16 v[80:95], v[214:217], v[116:119], v[80:95]
	v_add_f32_e32 v248, v154, v155
	v_cvt_pk_bf16_f32 v148, v148, v149
	v_cvt_pk_bf16_f32 v149, v150, v151
	v_cvt_pk_bf16_f32 v150, v152, v153
	v_cvt_pk_bf16_f32 v151, v154, v155
	v_mfma_f32_32x32x16_bf16 v[32:47], v[226:229], v[132:135], v[32:47]
	ds_read_b64_tr_b16 v[226:227], v211 offset:45056
	ds_read_b64_tr_b16 v[228:229], v211 offset:46592
	v_exp_f32_e32 v156, v156
	v_exp_f32_e32 v157, v157
	v_exp_f32_e32 v158, v158
	v_exp_f32_e32 v159, v159
	s_waitcnt lgkmcnt(6)
	v_mfma_f32_32x32x16_bf16 v[16:31], v[230:233], v[132:135], v[16:31]
	ds_read_b64_tr_b16 v[230:231], v211 offset:45120
	ds_read_b64_tr_b16 v[232:233], v211 offset:46656
	v_add_f32_e32 v213, v213, v248
	v_add_f32_e32 v15, v15, v213
	v_exp_f32_e32 v160, v160
	v_exp_f32_e32 v161, v161
	s_waitcnt lgkmcnt(6)
	v_mfma_f32_32x32x16_bf16 v[32:47], v[234:237], v[136:139], v[32:47]
	ds_read_b64_tr_b16 v[234:235], v211 offset:48128
	ds_read_b64_tr_b16 v[236:237], v211 offset:49664
	v_exp_f32_e32 v162, v162
	v_exp_f32_e32 v163, v163
	v_add_f32_e32 v213, v156, v157
	v_add_f32_e32 v248, v158, v159
	s_setprio 0
	s_waitcnt lgkmcnt(6)
	v_mfma_f32_32x32x16_bf16 v[16:31], v[238:241], v[136:139], v[16:31]
	ds_read_b64_tr_b16 v[238:239], v211 offset:48192
	ds_read_b64_tr_b16 v[240:241], v211 offset:49728
	s_cmp_lg_u32 s56, 0
	s_cbranch_scc1 .Lmla_mask1a
.Lmla_maskret1a:
	v_add_f32_e32 v249, v160, v161
	v_add_f32_e32 v250, v162, v163
	v_cvt_pk_bf16_f32 v152, v156, v157
	v_cvt_pk_bf16_f32 v153, v158, v159
	v_cvt_pk_bf16_f32 v154, v160, v161
	v_cvt_pk_bf16_f32 v155, v162, v163
	s_waitcnt lgkmcnt(6)
	v_mfma_f32_32x32x16_bf16 v[32:47], v[226:229], v[148:151], v[32:47]
	v_add_f32_e32 v213, v213, v248
	v_add_f32_e32 v249, v249, v250
	v_add_f32_e32 v14, v14, v15
	v_max3_f32 v251, v64, v65, v66
	v_max3_f32 v251, v251, v67, v68
	s_waitcnt lgkmcnt(4)
	v_mfma_f32_32x32x16_bf16 v[16:31], v[230:233], v[148:151], v[16:31]
	s_waitcnt vmcnt(4)
	ds_write_b128 v205, v[6:9] offset:25600
	ds_write_b128 v206, v[10:13] offset:13312
	ds_write_b128 v206, v[218:221] offset:19456
	v_add_f32_e32 v213, v213, v249
	v_add_f32_e32 v14, v14, v213
	v_add_f32_e32 v209, v209, v14
	v_max3_f32 v251, v251, v69, v70
	v_max3_f32 v251, v251, v71, v72
	v_max3_f32 v251, v251, v73, v74
	s_waitcnt lgkmcnt(5)
	v_mfma_f32_32x32x16_bf16 v[32:47], v[234:237], v[152:155], v[32:47]
	v_max3_f32 v251, v251, v75, v76
	v_max3_f32 v251, v251, v77, v78
	v_max_f32_e32 v251, v251, v79
	v_max3_f32 v252, v80, v81, v82
	v_max3_f32 v252, v252, v83, v84
	s_waitcnt lgkmcnt(3)
	v_mfma_f32_32x32x16_bf16 v[16:31], v[238:241], v[152:155], v[16:31]
	ds_write_b128 v207, v[2:5] offset:25728
	v_max3_f32 v252, v252, v85, v86
	v_max3_f32 v252, v252, v87, v88
	v_max3_f32 v252, v252, v89, v90
	v_max3_f32 v252, v252, v91, v92
	v_max3_f32 v252, v252, v93, v94
	v_max_f32_e32 v252, v252, v95
	v_max_f32_e32 v251, v251, v252
	v_mov_b32_e32 v252, v251
	s_nop 1
	v_permlane32_swap_b32_e32 v251, v252
	v_max_f32_e32 v251, v251, v252
	v_cmp_lt_f32_e32 vcc, 0x41000000, v251
	s_cmp_lg_u32 s26, 0
	s_cbranch_scc0 .Lmla_nr1a
	s_cbranch_vccnz .Lmla_rare1a

.Lmla_skip0a:
	s_waitcnt vmcnt(4)
	ds_write_b128 v205, v[120:123] offset:0
	ds_write_b128 v206, v[124:127] offset:38912
	ds_write_b128 v206, v[222:225] offset:45056
	ds_write_b128 v207, v[128:131] offset:128
	s_waitcnt lgkmcnt(0)
	s_barrier
	s_branch .Lmla_end0a

.Lmla_skip1a:
	s_waitcnt vmcnt(4)
	ds_write_b128 v205, v[6:9] offset:25600
	ds_write_b128 v206, v[10:13] offset:13312
	ds_write_b128 v206, v[218:221] offset:19456
	ds_write_b128 v207, v[2:5] offset:25728
	s_waitcnt lgkmcnt(0)
	s_barrier
	s_branch .Lmla_end1a

.Lmla_loopb:
.Lmla_it0b:
	s_add_i32 s42, s65, 3
	s_min_u32 s42, s42, s44
	s_lshl_b64 s[6:7], s[42:43], 17
	v_lshl_add_u64 v[242:243], v[190:191], 0, s[6:7]
	global_load_dwordx4 v[6:9], v[242:243], off
	s_cmp_ge_u32 s65, s45
	s_cbranch_scc1 .Lmla_skip0b
	s_add_i32 s41, s65, 1
	s_cmp_ge_u32 s41, s64
	s_cselect_b32 s7, 1, 0
	s_cmp_lt_u32 s41, s45
	s_cselect_b32 s26, 1, 0
	s_and_b32 s56, s7, s26
	s_lshl_b32 s27, s41, 6
	ds_read_b128 v[164:167], v210 offset:25600
	ds_read_b128 v[168:171], v210 offset:25632
	ds_read_b128 v[172:175], v210 offset:25664
	ds_read_b128 v[214:217], v210 offset:25696
	s_setprio 3
	v_exp_f32_e32 v64, v64
	v_exp_f32_e32 v65, v65
	v_exp_f32_e32 v66, v66
	v_exp_f32_e32 v67, v67
	s_waitcnt lgkmcnt(3)
	v_mfma_f32_32x32x16_bf16 v[132:147], v[164:167], v[96:99], v[48:63]
	ds_read_b128 v[164:167], v210 offset:25728
	v_add_f32_e32 v14, v64, v65
	v_add_f32_e32 v15, v66, v67
	v_exp_f32_e32 v68, v68
	v_exp_f32_e32 v69, v69
	s_waitcnt lgkmcnt(3)
	v_mfma_f32_32x32x16_bf16 v[132:147], v[168:171], v[100:103], v[132:147]
	ds_read_b128 v[168:171], v210 offset:25760
	v_exp_f32_e32 v70, v70
	v_exp_f32_e32 v71, v71
	v_add_f32_e32 v14, v14, v15
	v_add_f32_e32 v15, v68, v69
	s_waitcnt lgkmcnt(3)
	v_mfma_f32_32x32x16_bf16 v[132:147], v[172:175], v[104:107], v[132:147]
	ds_read_b128 v[172:175], v210 offset:32256
	v_add_f32_e32 v213, v70, v71
	v_cvt_pk_bf16_f32 v64, v64, v65
	v_cvt_pk_bf16_f32 v65, v66, v67
	v_cvt_pk_bf16_f32 v66, v68, v69
	v_cvt_pk_bf16_f32 v67, v70, v71
	s_waitcnt lgkmcnt(3)
	v_mfma_f32_32x32x16_bf16 v[132:147], v[214:217], v[108:111], v[132:147]
	ds_read_b128 v[214:217], v210 offset:32288
	v_exp_f32_e32 v72, v72
	v_exp_f32_e32 v73, v73
	v_exp_f32_e32 v74, v74
	v_exp_f32_e32 v75, v75
	s_waitcnt lgkmcnt(3)
	v_mfma_f32_32x32x16_bf16 v[132:147], v[164:167], v[112:115], v[132:147]
	ds_read_b128 v[164:167], v210 offset:32320
	v_add_f32_e32 v14, v14, v15
	v_add_f32_e32 v14, v14, v213
	v_exp_f32_e32 v76, v76
	v_exp_f32_e32 v77, v77
	s_setprio 2
	s_waitcnt lgkmcnt(3)
	v_mfma_f32_32x32x16_bf16 v[132:147], v[168:171], v[116:119], v[132:147]
	ds_read_b128 v[168:171], v210 offset:32352
	v_exp_f32_e32 v78, v78
	v_exp_f32_e32 v79, v79
	v_add_f32_e32 v15, v72, v73
	v_add_f32_e32 v213, v74, v75
	s_waitcnt lgkmcnt(3)
	v_mfma_f32_32x32x16_bf16 v[148:163], v[172:175], v[96:99], v[48:63]
	ds_read_b128 v[172:175], v210 offset:32384
	ds_read_b64_tr_b16 v[226:227], v211 offset:13312
	ds_read_b64_tr_b16 v[228:229], v211 offset:14848
	v_add_f32_e32 v248, v76, v77
	v_add_f32_e32 v249, v78, v79
	v_cvt_pk_bf16_f32 v68, v72, v73
	v_cvt_pk_bf16_f32 v69, v74, v75
	v_cvt_pk_bf16_f32 v70, v76, v77
	v_cvt_pk_bf16_f32 v71, v78, v79
	s_waitcnt lgkmcnt(5)
	v_mfma_f32_32x32x16_bf16 v[148:163], v[214:217], v[100:103], v[148:163]
	ds_read_b128 v[214:217], v210 offset:32416
	ds_read_b64_tr_b16 v[230:231], v211 offset:13376
	ds_read_b64_tr_b16 v[232:233], v211 offset:14912
	v_add_f32_e32 v15, v15, v213
	v_add_f32_e32 v248, v248, v249
	v_exp_f32_e32 v80, v80
	v_exp_f32_e32 v81, v81
	s_waitcnt lgkmcnt(7)
	v_mfma_f32_32x32x16_bf16 v[148:163], v[164:167], v[104:107], v[148:163]
	ds_read_b64_tr_b16 v[234:235], v211 offset:16384
	ds_read_b64_tr_b16 v[236:237], v211 offset:17920
	v_exp_f32_e32 v82, v82
	v_exp_f32_e32 v83, v83
	v_add_f32_e32 v14, v14, v15
	v_add_f32_e32 v14, v14, v248
	s_waitcnt lgkmcnt(8)
	v_mfma_f32_32x32x16_bf16 v[148:163], v[168:171], v[108:111], v[148:163]
	ds_read_b64_tr_b16 v[238:239], v211 offset:16448
	ds_read_b64_tr_b16 v[240:241], v211 offset:17984
	v_add_f32_e32 v15, v80, v81
	v_add_f32_e32 v213, v82, v83
	v_exp_f32_e32 v84, v84
	v_exp_f32_e32 v85, v85
	s_setprio 1
	s_waitcnt lgkmcnt(9)
	v_mfma_f32_32x32x16_bf16 v[148:163], v[172:175], v[112:115], v[148:163]
	v_exp_f32_e32 v86, v86
	v_exp_f32_e32 v87, v87
	v_add_f32_e32 v15, v15, v213
	v_add_f32_e32 v213, v84, v85
	s_waitcnt lgkmcnt(6)
	v_mfma_f32_32x32x16_bf16 v[148:163], v[214:217], v[116:119], v[148:163]
	v_add_f32_e32 v248, v86, v87
	v_cvt_pk_bf16_f32 v80, v80, v81
	v_cvt_pk_bf16_f32 v81, v82, v83
	v_cvt_pk_bf16_f32 v82, v84, v85
	v_cvt_pk_bf16_f32 v83, v86, v87
	v_mfma_f32_32x32x16_bf16 v[32:47], v[226:229], v[64:67], v[32:47]
	ds_read_b64_tr_b16 v[226:227], v211 offset:19456
	ds_read_b64_tr_b16 v[228:229], v211 offset:20992
	v_exp_f32_e32 v88, v88
	v_exp_f32_e32 v89, v89
	v_exp_f32_e32 v90, v90
	v_exp_f32_e32 v91, v91
	s_waitcnt lgkmcnt(6)
	v_mfma_f32_32x32x16_bf16 v[16:31], v[230:233], v[64:67], v[16:31]
	ds_read_b64_tr_b16 v[230:231], v211 offset:19520
	ds_read_b64_tr_b16 v[232:233], v211 offset:21056
	v_add_f32_e32 v213, v213, v248
	v_add_f32_e32 v15, v15, v213
	v_exp_f32_e32 v92, v92
	v_exp_f32_e32 v93, v93
	s_waitcnt lgkmcnt(6)
	v_mfma_f32_32x32x16_bf16 v[32:47], v[234:237], v[68:71], v[32:47]
	ds_read_b64_tr_b16 v[234:235], v211 offset:22528
	ds_read_b64_tr_b16 v[236:237], v211 offset:24064
	v_exp_f32_e32 v94, v94
	v_exp_f32_e32 v95, v95
	v_add_f32_e32 v213, v88, v89
	v_add_f32_e32 v248, v90, v91
	s_setprio 0
	s_waitcnt lgkmcnt(6)
	v_mfma_f32_32x32x16_bf16 v[16:31], v[238:241], v[68:71], v[16:31]
	ds_read_b64_tr_b16 v[238:239], v211 offset:22592
	ds_read_b64_tr_b16 v[240:241], v211 offset:24128
	s_cmp_lg_u32 s56, 0
	s_cbranch_scc1 .Lmla_mask0b
.Lmla_maskret0b:
	v_add_f32_e32 v249, v92, v93
	v_add_f32_e32 v250, v94, v95
	v_cvt_pk_bf16_f32 v84, v88, v89
	v_cvt_pk_bf16_f32 v85, v90, v91
	v_cvt_pk_bf16_f32 v86, v92, v93
	v_cvt_pk_bf16_f32 v87, v94, v95
	s_waitcnt lgkmcnt(6)
	v_mfma_f32_32x32x16_bf16 v[32:47], v[226:229], v[80:83], v[32:47]
	v_add_f32_e32 v213, v213, v248
	v_add_f32_e32 v249, v249, v250
	v_add_f32_e32 v14, v14, v15
	v_max3_f32 v251, v132, v133, v134
	v_max3_f32 v251, v251, v135, v136
	s_waitcnt lgkmcnt(4)
	v_mfma_f32_32x32x16_bf16 v[16:31], v[230:233], v[80:83], v[16:31]
	s_waitcnt vmcnt(1)
	ds_write_b128 v205, v[120:123] offset:0
	v_add_f32_e32 v213, v213, v249
	v_add_f32_e32 v14, v14, v213
	v_add_f32_e32 v209, v209, v14
	v_max3_f32 v251, v251, v137, v138
	v_max3_f32 v251, v251, v139, v140
	v_max3_f32 v251, v251, v141, v142
	s_waitcnt lgkmcnt(3)
	v_mfma_f32_32x32x16_bf16 v[32:47], v[234:237], v[84:87], v[32:47]
	v_max3_f32 v251, v251, v143, v144
	v_max3_f32 v251, v251, v145, v146
	v_max_f32_e32 v251, v251, v147
	v_max3_f32 v252, v148, v149, v150
	v_max3_f32 v252, v252, v151, v152
	s_waitcnt lgkmcnt(1)
	v_mfma_f32_32x32x16_bf16 v[16:31], v[238:241], v[84:87], v[16:31]
	v_max3_f32 v252, v252, v153, v154
	v_max3_f32 v252, v252, v155, v156
	v_max3_f32 v252, v252, v157, v158
	v_max3_f32 v252, v252, v159, v160
	v_max3_f32 v252, v252, v161, v162
	v_max_f32_e32 v252, v252, v163
	v_max_f32_e32 v251, v251, v252
	v_mov_b32_e32 v252, v251
	s_nop 1
	v_permlane32_swap_b32_e32 v251, v252
	v_max_f32_e32 v251, v251, v252
	v_cmp_lt_f32_e32 vcc, 0x41000000, v251
	s_cmp_lg_u32 s26, 0
	s_cbranch_scc0 .Lmla_nr0b
	s_cbranch_vccnz .Lmla_rare0b

.Lmla_end0b:
.Lmla_it1b:
	s_add_i32 s66, s65, 1
	s_add_i32 s42, s66, 3
	s_min_u32 s42, s42, s44
	s_lshl_b64 s[6:7], s[42:43], 17
	v_lshl_add_u64 v[242:243], v[190:191], 0, s[6:7]
	global_load_dwordx4 v[120:123], v[242:243], off
	s_cmp_ge_u32 s66, s45
	s_cbranch_scc1 .Lmla_skip1b
	s_add_i32 s41, s66, 1
	s_cmp_ge_u32 s41, s64
	s_cselect_b32 s7, 1, 0
	s_cmp_lt_u32 s41, s45
	s_cselect_b32 s26, 1, 0
	s_and_b32 s56, s7, s26
	s_lshl_b32 s27, s41, 6
	ds_read_b128 v[164:167], v210 offset:0
	ds_read_b128 v[168:171], v210 offset:32
	ds_read_b128 v[172:175], v210 offset:64
	ds_read_b128 v[214:217], v210 offset:96
	s_setprio 3
	v_exp_f32_e32 v132, v132
	v_exp_f32_e32 v133, v133
	v_exp_f32_e32 v134, v134
	v_exp_f32_e32 v135, v135
	s_waitcnt lgkmcnt(3)
	v_mfma_f32_32x32x16_bf16 v[64:79], v[164:167], v[96:99], v[48:63]
	ds_read_b128 v[164:167], v210 offset:128
	v_add_f32_e32 v14, v132, v133
	v_add_f32_e32 v15, v134, v135
	v_exp_f32_e32 v136, v136
	v_exp_f32_e32 v137, v137
	s_waitcnt lgkmcnt(3)
	v_mfma_f32_32x32x16_bf16 v[64:79], v[168:171], v[100:103], v[64:79]
	ds_read_b128 v[168:171], v210 offset:160
	v_exp_f32_e32 v138, v138
	v_exp_f32_e32 v139, v139
	v_add_f32_e32 v14, v14, v15
	v_add_f32_e32 v15, v136, v137
	s_waitcnt lgkmcnt(3)
	v_mfma_f32_32x32x16_bf16 v[64:79], v[172:175], v[104:107], v[64:79]
	ds_read_b128 v[172:175], v210 offset:6656
	v_add_f32_e32 v213, v138, v139
	v_cvt_pk_bf16_f32 v132, v132, v133
	v_cvt_pk_bf16_f32 v133, v134, v135
	v_cvt_pk_bf16_f32 v134, v136, v137
	v_cvt_pk_bf16_f32 v135, v138, v139
	s_waitcnt lgkmcnt(3)
	v_mfma_f32_32x32x16_bf16 v[64:79], v[214:217], v[108:111], v[64:79]
	ds_read_b128 v[214:217], v210 offset:6688
	v_exp_f32_e32 v140, v140
	v_exp_f32_e32 v141, v141
	v_exp_f32_e32 v142, v142
	v_exp_f32_e32 v143, v143
	s_waitcnt lgkmcnt(3)
	v_mfma_f32_32x32x16_bf16 v[64:79], v[164:167], v[112:115], v[64:79]
	ds_read_b128 v[164:167], v210 offset:6720
	v_add_f32_e32 v14, v14, v15
	v_add_f32_e32 v14, v14, v213
	v_exp_f32_e32 v144, v144
	v_exp_f32_e32 v145, v145
	s_setprio 2
	s_waitcnt lgkmcnt(3)
	v_mfma_f32_32x32x16_bf16 v[64:79], v[168:171], v[116:119], v[64:79]
	ds_read_b128 v[168:171], v210 offset:6752
	v_exp_f32_e32 v146, v146
	v_exp_f32_e32 v147, v147
	v_add_f32_e32 v15, v140, v141
	v_add_f32_e32 v213, v142, v143
	s_waitcnt lgkmcnt(3)
	v_mfma_f32_32x32x16_bf16 v[80:95], v[172:175], v[96:99], v[48:63]
	ds_read_b128 v[172:175], v210 offset:6784
	ds_read_b64_tr_b16 v[226:227], v211 offset:38912
	ds_read_b64_tr_b16 v[228:229], v211 offset:40448
	v_add_f32_e32 v248, v144, v145
	v_add_f32_e32 v249, v146, v147
	v_cvt_pk_bf16_f32 v136, v140, v141
	v_cvt_pk_bf16_f32 v137, v142, v143
	v_cvt_pk_bf16_f32 v138, v144, v145
	v_cvt_pk_bf16_f32 v139, v146, v147
	s_waitcnt lgkmcnt(5)
	v_mfma_f32_32x32x16_bf16 v[80:95], v[214:217], v[100:103], v[80:95]
	ds_read_b128 v[214:217], v210 offset:6816
	ds_read_b64_tr_b16 v[230:231], v211 offset:38976
	ds_read_b64_tr_b16 v[232:233], v211 offset:40512
	v_add_f32_e32 v15, v15, v213
	v_add_f32_e32 v248, v248, v249
	v_exp_f32_e32 v148, v148
	v_exp_f32_e32 v149, v149
	s_waitcnt lgkmcnt(7)
	v_mfma_f32_32x32x16_bf16 v[80:95], v[164:167], v[104:107], v[80:95]
	ds_read_b64_tr_b16 v[234:235], v211 offset:41984
	ds_read_b64_tr_b16 v[236:237], v211 offset:43520
	v_exp_f32_e32 v150, v150
	v_exp_f32_e32 v151, v151
	v_add_f32_e32 v14, v14, v15
	v_add_f32_e32 v14, v14, v248
	s_waitcnt lgkmcnt(8)
	v_mfma_f32_32x32x16_bf16 v[80:95], v[168:171], v[108:111], v[80:95]
	ds_read_b64_tr_b16 v[238:239], v211 offset:42048
	ds_read_b64_tr_b16 v[240:241], v211 offset:43584
	v_add_f32_e32 v15, v148, v149
	v_add_f32_e32 v213, v150, v151
	v_exp_f32_e32 v152, v152
	v_exp_f32_e32 v153, v153
	s_setprio 1
	s_waitcnt lgkmcnt(9)
	v_mfma_f32_32x32x16_bf16 v[80:95], v[172:175], v[112:115], v[80:95]
	v_exp_f32_e32 v154, v154
	v_exp_f32_e32 v155, v155
	v_add_f32_e32 v15, v15, v213
	v_add_f32_e32 v213, v152, v153
	s_waitcnt lgkmcnt(6)
	v_mfma_f32_32x32x16_bf16 v[80:95], v[214:217], v[116:119], v[80:95]
	v_add_f32_e32 v248, v154, v155
	v_cvt_pk_bf16_f32 v148, v148, v149
	v_cvt_pk_bf16_f32 v149, v150, v151
	v_cvt_pk_bf16_f32 v150, v152, v153
	v_cvt_pk_bf16_f32 v151, v154, v155
	v_mfma_f32_32x32x16_bf16 v[32:47], v[226:229], v[132:135], v[32:47]
	ds_read_b64_tr_b16 v[226:227], v211 offset:45056
	ds_read_b64_tr_b16 v[228:229], v211 offset:46592
	v_exp_f32_e32 v156, v156
	v_exp_f32_e32 v157, v157
	v_exp_f32_e32 v158, v158
	v_exp_f32_e32 v159, v159
	s_waitcnt lgkmcnt(6)
	v_mfma_f32_32x32x16_bf16 v[16:31], v[230:233], v[132:135], v[16:31]
	ds_read_b64_tr_b16 v[230:231], v211 offset:45120
	ds_read_b64_tr_b16 v[232:233], v211 offset:46656
	v_add_f32_e32 v213, v213, v248
	v_add_f32_e32 v15, v15, v213
	v_exp_f32_e32 v160, v160
	v_exp_f32_e32 v161, v161
	s_waitcnt lgkmcnt(6)
	v_mfma_f32_32x32x16_bf16 v[32:47], v[234:237], v[136:139], v[32:47]
	ds_read_b64_tr_b16 v[234:235], v211 offset:48128
	ds_read_b64_tr_b16 v[236:237], v211 offset:49664
	v_exp_f32_e32 v162, v162
	v_exp_f32_e32 v163, v163
	v_add_f32_e32 v213, v156, v157
	v_add_f32_e32 v248, v158, v159
	s_setprio 0
	s_waitcnt lgkmcnt(6)
	v_mfma_f32_32x32x16_bf16 v[16:31], v[238:241], v[136:139], v[16:31]
	ds_read_b64_tr_b16 v[238:239], v211 offset:48192
	ds_read_b64_tr_b16 v[240:241], v211 offset:49728
	s_cmp_lg_u32 s56, 0
	s_cbranch_scc1 .Lmla_mask1b
.Lmla_maskret1b:
	v_add_f32_e32 v249, v160, v161
	v_add_f32_e32 v250, v162, v163
	v_cvt_pk_bf16_f32 v152, v156, v157
	v_cvt_pk_bf16_f32 v153, v158, v159
	v_cvt_pk_bf16_f32 v154, v160, v161
	v_cvt_pk_bf16_f32 v155, v162, v163
	s_waitcnt lgkmcnt(6)
	v_mfma_f32_32x32x16_bf16 v[32:47], v[226:229], v[148:151], v[32:47]
	v_add_f32_e32 v213, v213, v248
	v_add_f32_e32 v249, v249, v250
	v_add_f32_e32 v14, v14, v15
	v_max3_f32 v251, v64, v65, v66
	v_max3_f32 v251, v251, v67, v68
	s_waitcnt lgkmcnt(4)
	v_mfma_f32_32x32x16_bf16 v[16:31], v[230:233], v[148:151], v[16:31]
	s_waitcnt vmcnt(1)
	ds_write_b128 v205, v[6:9] offset:25600
	v_add_f32_e32 v213, v213, v249
	v_add_f32_e32 v14, v14, v213
	v_add_f32_e32 v209, v209, v14
	v_max3_f32 v251, v251, v69, v70
	v_max3_f32 v251, v251, v71, v72
	v_max3_f32 v251, v251, v73, v74
	s_waitcnt lgkmcnt(3)
	v_mfma_f32_32x32x16_bf16 v[32:47], v[234:237], v[152:155], v[32:47]
	v_max3_f32 v251, v251, v75, v76
	v_max3_f32 v251, v251, v77, v78
	v_max_f32_e32 v251, v251, v79
	v_max3_f32 v252, v80, v81, v82
	v_max3_f32 v252, v252, v83, v84
	s_waitcnt lgkmcnt(1)
	v_mfma_f32_32x32x16_bf16 v[16:31], v[238:241], v[152:155], v[16:31]
	v_max3_f32 v252, v252, v85, v86
	v_max3_f32 v252, v252, v87, v88
	v_max3_f32 v252, v252, v89, v90
	v_max3_f32 v252, v252, v91, v92
	v_max3_f32 v252, v252, v93, v94
	v_max_f32_e32 v252, v252, v95
	v_max_f32_e32 v251, v251, v252
	v_mov_b32_e32 v252, v251
	s_nop 1
	v_permlane32_swap_b32_e32 v251, v252
	v_max_f32_e32 v251, v251, v252
	v_cmp_lt_f32_e32 vcc, 0x41000000, v251
	s_cmp_lg_u32 s26, 0
	s_cbranch_scc0 .Lmla_nr1b
	s_cbranch_vccnz .Lmla_rare1b

.Lmla_skip0b:
	s_waitcnt vmcnt(1)
	ds_write_b128 v205, v[120:123] offset:0
	s_waitcnt lgkmcnt(0)
	s_barrier
	s_branch .Lmla_end0b

.Lmla_skip1b:
	s_waitcnt vmcnt(1)
	ds_write_b128 v205, v[6:9] offset:25600
	s_waitcnt lgkmcnt(0)
	s_barrier
	s_branch .Lmla_end1b
